# mixers-phase transposes on blocks>=128 instead of >=160
# speedup vs baseline: 1.0058x; 1.0058x over previous
.LBB0_493:
	s_cmp_lt_u32 s96, 128
	s_cbranch_scc1 .Lmix0_skip
	s_load_dwordx2 s[0:1], s[92:93], 0x58
	s_load_dwordx2 s[2:3], s[92:93], 0xb8
	s_load_dwordx2 s[4:5], s[92:93], 0xc0
	s_load_dwordx2 s[6:7], s[92:93], 0xc8
	s_load_dwordx2 s[8:9], s[92:93], 0xd0
	s_load_dwordx2 s[10:11], s[92:93], 0xe8
	v_and_b32_e32 v74, 63, v154
	v_lshrrev_b32_e32 v75, 6, v154
	v_mul_u32_u24_e32 v75, 0x2100, v75
	v_lshrrev_b32_e32 v3, 5, v74
	v_and_b32_e32 v4, 31, v74
	v_lshlrev_b32_e32 v4, 2, v4
	v_lshrrev_b32_e32 v5, 3, v74
	v_and_b32_e32 v6, 7, v74
	v_mul_u32_u24_e32 v2, 264, v6
	v_add_u32_e32 v2, v2, v5
	v_lshl_add_u32 v2, v2, 2, v75
	v_lshlrev_b32_e32 v6, 4, v6
	v_mul_u32_u24_e32 v1, 132, v5
	v_add3_u32 v1, v1, v6, v75
	v_readfirstlane_b32 s13, v154
	s_lshr_b32 s13, s13, 6
	s_lshl_b32 s26, s96, 3
	s_add_u32 s13, s13, s26
	s_sub_u32 s12, s13, 1024
	s_add_u32 s12, s12, 12288
	s_waitcnt lgkmcnt(0)
	s_cmp_ge_u32 s12, 33280
	s_cbranch_scc1 .Ltrm_done
	s_cmp_ge_u32 s12, 33280
	s_cselect_b32 s41, 1, 0
	s_cselect_b32 s26, 33280, 0
	s_sub_u32 s42, s12, s26
	s_cmp_ge_u32 s42, 12288
	s_cbranch_scc1 .Ltrm_m2
	s_mul_i32 s43, s42, 43691
	s_lshr_b32 s43, s43, 24
	s_mul_i32 s26, s43, 384
	s_sub_u32 s44, s42, s26
	s_mov_b32 s14, s0
	s_mov_b32 s15, s1
	s_mov_b32 s36, 0xc000
	s_mov_b32 s37, 0x6000000
	s_mov_b32 s38, 0x0
	s_mov_b32 s39, 0x3000000
	s_mov_b32 s40, 0x1000
	s_branch .Ltrm_dec_done1

.Ltrm_loop:
	s_add_u32 s12, s12, 1024
	s_cmp_lt_u32 s12, 33280
	s_cselect_b32 s24, 1, 0
	s_cbranch_scc0 .Ltrm_nonext8
	s_cmp_ge_u32 s12, 33280
	s_cselect_b32 s41, 1, 0
	s_cselect_b32 s26, 33280, 0
	s_sub_u32 s42, s12, s26
	s_cmp_ge_u32 s42, 12288
	s_cbranch_scc1 .Ltrm_m11
	s_mul_i32 s43, s42, 43691
	s_lshr_b32 s43, s43, 24
	s_mul_i32 s26, s43, 384
	s_sub_u32 s44, s42, s26
	s_mov_b32 s16, s0
	s_mov_b32 s17, s1
	s_mov_b32 s36, 0xc000
	s_mov_b32 s37, 0x6000000
	s_mov_b32 s38, 0x0
	s_mov_b32 s39, 0x3000000
	s_mov_b32 s40, 0x1000
	s_branch .Ltrm_dec_done10

.Ltrm_after9:
	ds_write_b32 v1, v10 offset:0
	ds_write_b32 v1, v11 offset:4
	ds_write_b32 v1, v12 offset:8
	ds_write_b32 v1, v13 offset:12
	ds_write_b32 v1, v14 offset:1056
	ds_write_b32 v1, v15 offset:1060
	ds_write_b32 v1, v16 offset:1064
	ds_write_b32 v1, v17 offset:1068
	ds_write_b32 v1, v18 offset:2112
	ds_write_b32 v1, v19 offset:2116
	ds_write_b32 v1, v20 offset:2120
	ds_write_b32 v1, v21 offset:2124
	ds_write_b32 v1, v22 offset:3168
	ds_write_b32 v1, v23 offset:3172
	ds_write_b32 v1, v24 offset:3176
	ds_write_b32 v1, v25 offset:3180
	ds_write_b32 v1, v26 offset:4224
	ds_write_b32 v1, v27 offset:4228
	ds_write_b32 v1, v28 offset:4232
	ds_write_b32 v1, v29 offset:4236
	ds_write_b32 v1, v30 offset:5280
	ds_write_b32 v1, v31 offset:5284
	ds_write_b32 v1, v32 offset:5288
	ds_write_b32 v1, v33 offset:5292
	ds_write_b32 v1, v34 offset:6336
	ds_write_b32 v1, v35 offset:6340
	ds_write_b32 v1, v36 offset:6344
	ds_write_b32 v1, v37 offset:6348
	ds_write_b32 v1, v38 offset:7392
	ds_write_b32 v1, v39 offset:7396
	ds_write_b32 v1, v40 offset:7400
	ds_write_b32 v1, v41 offset:7404
	v_mad_u32_u24 v9, v5, s22, v6
	s_lshl_b32 s46, s22, 3
	s_waitcnt lgkmcnt(0)
	ds_read_b32 v74, v2 offset:0
	ds_read_b32 v75, v2 offset:132
	ds_read_b32 v76, v2 offset:264
	ds_read_b32 v77, v2 offset:396
	ds_read_b32 v78, v2 offset:528
	ds_read_b32 v79, v2 offset:660
	ds_read_b32 v80, v2 offset:792
	ds_read_b32 v81, v2 offset:924
	ds_read_b32 v82, v2 offset:32
	ds_read_b32 v83, v2 offset:164
	ds_read_b32 v84, v2 offset:296
	ds_read_b32 v85, v2 offset:428
	ds_read_b32 v86, v2 offset:560
	ds_read_b32 v87, v2 offset:692
	ds_read_b32 v88, v2 offset:824
	ds_read_b32 v89, v2 offset:956
	s_waitcnt lgkmcnt(8)
	v_cvt_pk_bf16_f32 v106, v74, v75
	v_cvt_pk_bf16_f32 v107, v76, v77
	v_cvt_pk_bf16_f32 v108, v78, v79
	v_cvt_pk_bf16_f32 v109, v80, v81
	global_store_dwordx4 v9, v[106:109], s[18:19]
	s_add_u32 s18, s18, s46
	s_addc_u32 s19, s19, 0
	ds_read_b32 v90, v2 offset:64
	ds_read_b32 v91, v2 offset:196
	ds_read_b32 v92, v2 offset:328
	ds_read_b32 v93, v2 offset:460
	ds_read_b32 v94, v2 offset:592
	ds_read_b32 v95, v2 offset:724
	ds_read_b32 v96, v2 offset:856
	ds_read_b32 v97, v2 offset:988
	s_waitcnt lgkmcnt(8)
	v_cvt_pk_bf16_f32 v110, v82, v83
	v_cvt_pk_bf16_f32 v111, v84, v85
	v_cvt_pk_bf16_f32 v112, v86, v87
	v_cvt_pk_bf16_f32 v113, v88, v89
	global_store_dwordx4 v9, v[110:113], s[18:19]
	s_add_u32 s18, s18, s46
	s_addc_u32 s19, s19, 0
	ds_read_b32 v98, v2 offset:96
	ds_read_b32 v99, v2 offset:228
	ds_read_b32 v100, v2 offset:360
	ds_read_b32 v101, v2 offset:492
	ds_read_b32 v102, v2 offset:624
	ds_read_b32 v103, v2 offset:756
	ds_read_b32 v104, v2 offset:888
	ds_read_b32 v105, v2 offset:1020
	s_waitcnt lgkmcnt(8)
	v_cvt_pk_bf16_f32 v106, v90, v91
	v_cvt_pk_bf16_f32 v107, v92, v93
	v_cvt_pk_bf16_f32 v108, v94, v95
	v_cvt_pk_bf16_f32 v109, v96, v97
	global_store_dwordx4 v9, v[106:109], s[18:19]
	s_add_u32 s18, s18, s46
	s_addc_u32 s19, s19, 0
	s_waitcnt lgkmcnt(0)
	v_cvt_pk_bf16_f32 v110, v98, v99
	v_cvt_pk_bf16_f32 v111, v100, v101
	v_cvt_pk_bf16_f32 v112, v102, v103
	v_cvt_pk_bf16_f32 v113, v104, v105
	global_store_dwordx4 v9, v[110:113], s[18:19]
	s_cmp_eq_u32 s24, 0
	s_cbranch_scc1 .Ltrm_done
	s_add_u32 s12, s12, 1024
	s_cmp_lt_u32 s12, 33280
	s_cselect_b32 s24, 1, 0
	s_cbranch_scc0 .Ltrm_nonext17
	s_cmp_ge_u32 s12, 33280
	s_cselect_b32 s41, 1, 0
	s_cselect_b32 s26, 33280, 0
	s_sub_u32 s42, s12, s26
	s_cmp_ge_u32 s42, 12288
	s_cbranch_scc1 .Ltrm_m20
	s_mul_i32 s43, s42, 43691
	s_lshr_b32 s43, s43, 24
	s_mul_i32 s26, s43, 384
	s_sub_u32 s44, s42, s26
	s_mov_b32 s14, s0
	s_mov_b32 s15, s1
	s_mov_b32 s36, 0xc000
	s_mov_b32 s37, 0x6000000
	s_mov_b32 s38, 0x0
	s_mov_b32 s39, 0x3000000
	s_mov_b32 s40, 0x1000
	s_branch .Ltrm_dec_done19

.LBB0_1734:
	s_cmp_lt_u32 s96, 128
	s_cbranch_scc1 .Lmix1_skip
	s_load_dwordx2 s[0:1], s[92:93], 0x58
	s_load_dwordx2 s[2:3], s[92:93], 0xb8
	s_load_dwordx2 s[4:5], s[92:93], 0xc0
	s_load_dwordx2 s[6:7], s[92:93], 0xc8
	s_load_dwordx2 s[8:9], s[92:93], 0xd0
	s_load_dwordx2 s[10:11], s[92:93], 0xe8
	v_and_b32_e32 v74, 63, v154
	v_lshrrev_b32_e32 v75, 6, v154
	v_mul_u32_u24_e32 v75, 0x2100, v75
	v_lshrrev_b32_e32 v3, 5, v74
	v_and_b32_e32 v4, 31, v74
	v_lshlrev_b32_e32 v4, 2, v4
	v_lshrrev_b32_e32 v5, 3, v74
	v_and_b32_e32 v6, 7, v74
	v_mul_u32_u24_e32 v2, 264, v6
	v_add_u32_e32 v2, v2, v5
	v_lshl_add_u32 v2, v2, 2, v75
	v_lshlrev_b32_e32 v6, 4, v6
	v_mul_u32_u24_e32 v1, 132, v5
	v_add3_u32 v1, v1, v6, v75
	v_readfirstlane_b32 s13, v154
	s_lshr_b32 s13, s13, 6
	s_lshl_b32 s26, s96, 3
	s_add_u32 s13, s13, s26
	s_sub_u32 s12, s13, 1024
	s_add_u32 s12, s12, 49664
	s_waitcnt lgkmcnt(0)
	s_cmp_ge_u32 s12, 60928
	s_cbranch_scc1 .Ltrn_done
	s_cmp_ge_u32 s12, 33280
	s_cselect_b32 s41, 1, 0
	s_cselect_b32 s26, 33280, 0
	s_sub_u32 s42, s12, s26
	s_cmp_ge_u32 s42, 12288
	s_cbranch_scc1 .Ltrn_m2
	s_mul_i32 s43, s42, 43691
	s_lshr_b32 s43, s43, 24
	s_mul_i32 s26, s43, 384
	s_sub_u32 s44, s42, s26
	s_mov_b32 s14, s0
	s_mov_b32 s15, s1
	s_mov_b32 s36, 0xc000
	s_mov_b32 s37, 0x6000000
	s_mov_b32 s38, 0x0
	s_mov_b32 s39, 0x3000000
	s_mov_b32 s40, 0x1000
	s_branch .Ltrn_dec_done1
